# LN epilogues: fp32 X tile stored with plain stores again (only the bf16 H tile, which other workgroups wait for, is write-through)
# speedup vs baseline: 1.0033x; 1.0033x over previous
.Lln1_pok1:
	v_add_f32_e32 v250, v250, v226
	v_add_f32_e32 v252, v252, v228
	v_add_f32_e32 v250, v250, v230
	v_add_f32_e32 v252, v252, v232
	v_add_f32_e32 v250, v250, v234
	v_add_f32_e32 v252, v252, v236
	v_add_f32_e32 v250, v250, v238
	v_add_f32_e32 v252, v252, v240
	v_add_f32_e32 v250, v250, v206
	v_add_f32_e32 v252, v252, v208
	v_add_f32_e32 v250, v250, v210
	v_add_f32_e32 v252, v252, v212
	v_add_f32_e32 v250, v250, v214
	v_add_f32_e32 v252, v252, v216
	v_add_f32_e32 v250, v250, v218
	v_add_f32_e32 v252, v252, v220
	global_load_dwordx4 v[226:229], v246, s[22:23]
	global_load_dwordx4 v[230:233], v246, s[22:23] offset:64
	global_load_dwordx4 v[234:237], v246, s[22:23] offset:128
	global_load_dwordx4 v[238:241], v246, s[22:23] offset:192
	v_mov_b32_e32 v206, v250
	v_mov_b32_e32 v207, v252
	v_mul_f32_e32 v208, 0x3a800000, v206
	v_mul_f32_e32 v209, v208, v208
	v_mov_b32_e32 v216, 0x3a800000
	v_fma_f32 v209, v207, v216, -v209
	v_max_f32_e32 v209, 0, v209
	v_add_f32_e32 v209, 0x3727c5ac, v209
	v_rsq_f32_e32 v209, v209
	v_mov_b32_e32 v210, v208
	v_mov_b32_e32 v211, v208
	v_mov_b32_e32 v214, v209
	v_mov_b32_e32 v215, v209
	s_nop 1
	v_permlane16_swap_b32_e32 v210, v211
	v_permlane16_swap_b32_e32 v214, v215
	v_mov_b32_e32 v212, v210
	v_mov_b32_e32 v213, v211
	v_mov_b32_e32 v216, v214
	v_mov_b32_e32 v217, v215
	s_nop 1
	v_permlane32_swap_b32_e32 v210, v212
	v_permlane32_swap_b32_e32 v211, v213
	v_permlane32_swap_b32_e32 v214, v216
	v_permlane32_swap_b32_e32 v215, v217
	v_readfirstlane_b32 s64, v137
	s_lshr_b32 s64, s64, 6
	s_lshl_b32 s64, s64, 14
	v_and_b32_e32 v222, 63, v137
	v_and_b32_e32 v246, 15, v222
	v_lshrrev_b32_e32 v247, 4, v222
	v_and_b32_e32 v248, 3, v246
	v_xor_b32_e32 v248, v248, v247
	v_lshlrev_b32_e32 v248, 4, v248
	v_lshl_add_u32 v248, v246, 8, v248
	v_add_u32_e32 v248, s64, v248
	v_lshl_add_u32 v249, v222, 4, s64
	v_add_u32_e32 v250, s36, v247
	v_lshlrev_b32_e32 v250, 12, v250
	v_xor_b32_e32 v251, v246, v247
	v_lshl_add_u32 v250, v251, 4, v250
	s_lshl_b32 s65, s37, 2
	v_add_u32_e32 v250, s65, v250
	v_sub_f32_e32 v62, v62, v210
	v_sub_f32_e32 v63, v63, v210
	v_sub_f32_e32 v64, v64, v210
	v_sub_f32_e32 v65, v65, v210
	v_mul_f32_e32 v62, v214, v62
	v_mul_f32_e32 v63, v214, v63
	v_mul_f32_e32 v64, v214, v64
	v_mul_f32_e32 v65, v214, v65
	v_fma_f32 v62, v66, v62, v90
	v_fma_f32 v63, v67, v63, v91
	v_fma_f32 v64, v68, v64, v92
	v_fma_f32 v65, v69, v65, v93
	ds_write_b128 v248, v[62:65] offset:0
	v_sub_f32_e32 v86, v86, v210
	v_sub_f32_e32 v87, v87, v210
	v_sub_f32_e32 v88, v88, v210
	v_sub_f32_e32 v89, v89, v210
	v_mul_f32_e32 v86, v214, v86
	v_mul_f32_e32 v87, v214, v87
	v_mul_f32_e32 v88, v214, v88
	v_mul_f32_e32 v89, v214, v89
	v_fma_f32 v86, v74, v86, v94
	v_fma_f32 v87, v75, v87, v95
	v_fma_f32 v88, v76, v88, v96
	v_fma_f32 v89, v77, v89, v97
	ds_write_b128 v248, v[86:89] offset:64
	v_sub_f32_e32 v70, v70, v210
	v_sub_f32_e32 v71, v71, v210
	v_sub_f32_e32 v72, v72, v210
	v_sub_f32_e32 v73, v73, v210
	v_mul_f32_e32 v70, v214, v70
	v_mul_f32_e32 v71, v214, v71
	v_mul_f32_e32 v72, v214, v72
	v_mul_f32_e32 v73, v214, v73
	v_fma_f32 v70, v78, v70, v108
	v_fma_f32 v71, v79, v71, v109
	v_fma_f32 v72, v80, v72, v110
	v_fma_f32 v73, v81, v73, v111
	ds_write_b128 v248, v[70:73] offset:128
	v_sub_f32_e32 v176, v176, v210
	v_sub_f32_e32 v177, v177, v210
	v_sub_f32_e32 v178, v178, v210
	v_sub_f32_e32 v179, v179, v210
	v_mul_f32_e32 v176, v214, v176
	v_mul_f32_e32 v177, v214, v177
	v_mul_f32_e32 v178, v214, v178
	v_mul_f32_e32 v179, v214, v179
	v_fma_f32 v176, v82, v176, v172
	v_fma_f32 v177, v83, v177, v173
	v_fma_f32 v178, v84, v178, v174
	v_fma_f32 v179, v85, v179, v175
	ds_write_b128 v248, v[176:179] offset:192
	v_sub_f32_e32 v202, v202, v211
	v_sub_f32_e32 v203, v203, v211
	v_sub_f32_e32 v204, v204, v211
	v_sub_f32_e32 v205, v205, v211
	v_mul_f32_e32 v202, v215, v202
	v_mul_f32_e32 v203, v215, v203
	v_mul_f32_e32 v204, v215, v204
	v_mul_f32_e32 v205, v215, v205
	v_fma_f32 v202, v66, v202, v90
	v_fma_f32 v203, v67, v203, v91
	v_fma_f32 v204, v68, v204, v92
	v_fma_f32 v205, v69, v205, v93
	ds_write_b128 v248, v[202:205] offset:4096
	v_sub_f32_e32 v54, v54, v211
	v_sub_f32_e32 v55, v55, v211
	v_sub_f32_e32 v56, v56, v211
	v_sub_f32_e32 v57, v57, v211
	v_mul_f32_e32 v54, v215, v54
	v_mul_f32_e32 v55, v215, v55
	v_mul_f32_e32 v56, v215, v56
	v_mul_f32_e32 v57, v215, v57
	v_fma_f32 v54, v74, v54, v94
	v_fma_f32 v55, v75, v55, v95
	v_fma_f32 v56, v76, v56, v96
	v_fma_f32 v57, v77, v57, v97
	ds_write_b128 v248, v[54:57] offset:4160
	v_sub_f32_e32 v58, v58, v211
	v_sub_f32_e32 v59, v59, v211
	v_sub_f32_e32 v60, v60, v211
	v_sub_f32_e32 v61, v61, v211
	v_mul_f32_e32 v58, v215, v58
	v_mul_f32_e32 v59, v215, v59
	v_mul_f32_e32 v60, v215, v60
	v_mul_f32_e32 v61, v215, v61
	v_fma_f32 v58, v78, v58, v108
	v_fma_f32 v59, v79, v59, v109
	v_fma_f32 v60, v80, v60, v110
	v_fma_f32 v61, v81, v61, v111
	ds_write_b128 v248, v[58:61] offset:4224
	v_sub_f32_e32 v34, v34, v211
	v_sub_f32_e32 v35, v35, v211
	v_sub_f32_e32 v36, v36, v211
	v_sub_f32_e32 v37, v37, v211
	v_mul_f32_e32 v34, v215, v34
	v_mul_f32_e32 v35, v215, v35
	v_mul_f32_e32 v36, v215, v36
	v_mul_f32_e32 v37, v215, v37
	v_fma_f32 v34, v82, v34, v172
	v_fma_f32 v35, v83, v35, v173
	v_fma_f32 v36, v84, v36, v174
	v_fma_f32 v37, v85, v37, v175
	ds_write_b128 v248, v[34:37] offset:4288
	v_sub_f32_e32 v30, v30, v212
	v_sub_f32_e32 v31, v31, v212
	v_sub_f32_e32 v32, v32, v212
	v_sub_f32_e32 v33, v33, v212
	v_mul_f32_e32 v30, v216, v30
	v_mul_f32_e32 v31, v216, v31
	v_mul_f32_e32 v32, v216, v32
	v_mul_f32_e32 v33, v216, v33
	v_fma_f32 v30, v66, v30, v90
	v_fma_f32 v31, v67, v31, v91
	v_fma_f32 v32, v68, v32, v92
	v_fma_f32 v33, v69, v33, v93
	ds_write_b128 v248, v[30:33] offset:8192
	v_sub_f32_e32 v26, v26, v212
	v_sub_f32_e32 v27, v27, v212
	v_sub_f32_e32 v28, v28, v212
	v_sub_f32_e32 v29, v29, v212
	v_mul_f32_e32 v26, v216, v26
	v_mul_f32_e32 v27, v216, v27
	v_mul_f32_e32 v28, v216, v28
	v_mul_f32_e32 v29, v216, v29
	v_fma_f32 v26, v74, v26, v94
	v_fma_f32 v27, v75, v27, v95
	v_fma_f32 v28, v76, v28, v96
	v_fma_f32 v29, v77, v29, v97
	ds_write_b128 v248, v[26:29] offset:8256
	v_sub_f32_e32 v22, v22, v212
	v_sub_f32_e32 v23, v23, v212
	v_sub_f32_e32 v24, v24, v212
	v_sub_f32_e32 v25, v25, v212
	v_mul_f32_e32 v22, v216, v22
	v_mul_f32_e32 v23, v216, v23
	v_mul_f32_e32 v24, v216, v24
	v_mul_f32_e32 v25, v216, v25
	v_fma_f32 v22, v78, v22, v108
	v_fma_f32 v23, v79, v23, v109
	v_fma_f32 v24, v80, v24, v110
	v_fma_f32 v25, v81, v25, v111
	ds_write_b128 v248, v[22:25] offset:8320
	v_sub_f32_e32 v18, v18, v212
	v_sub_f32_e32 v19, v19, v212
	v_sub_f32_e32 v20, v20, v212
	v_sub_f32_e32 v21, v21, v212
	v_mul_f32_e32 v18, v216, v18
	v_mul_f32_e32 v19, v216, v19
	v_mul_f32_e32 v20, v216, v20
	v_mul_f32_e32 v21, v216, v21
	v_fma_f32 v18, v82, v18, v172
	v_fma_f32 v19, v83, v19, v173
	v_fma_f32 v20, v84, v20, v174
	v_fma_f32 v21, v85, v21, v175
	ds_write_b128 v248, v[18:21] offset:8384
	v_sub_f32_e32 v14, v14, v213
	v_sub_f32_e32 v15, v15, v213
	v_sub_f32_e32 v16, v16, v213
	v_sub_f32_e32 v17, v17, v213
	v_mul_f32_e32 v14, v217, v14
	v_mul_f32_e32 v15, v217, v15
	v_mul_f32_e32 v16, v217, v16
	v_mul_f32_e32 v17, v217, v17
	v_fma_f32 v14, v66, v14, v90
	v_fma_f32 v15, v67, v15, v91
	v_fma_f32 v16, v68, v16, v92
	v_fma_f32 v17, v69, v17, v93
	ds_write_b128 v248, v[14:17] offset:12288
	v_sub_f32_e32 v10, v10, v213
	v_sub_f32_e32 v11, v11, v213
	v_sub_f32_e32 v12, v12, v213
	v_sub_f32_e32 v13, v13, v213
	v_mul_f32_e32 v10, v217, v10
	v_mul_f32_e32 v11, v217, v11
	v_mul_f32_e32 v12, v217, v12
	v_mul_f32_e32 v13, v217, v13
	v_fma_f32 v10, v74, v10, v94
	v_fma_f32 v11, v75, v11, v95
	v_fma_f32 v12, v76, v12, v96
	v_fma_f32 v13, v77, v13, v97
	ds_write_b128 v248, v[10:13] offset:12352
	v_sub_f32_e32 v6, v6, v213
	v_sub_f32_e32 v7, v7, v213
	v_sub_f32_e32 v8, v8, v213
	v_sub_f32_e32 v9, v9, v213
	v_mul_f32_e32 v6, v217, v6
	v_mul_f32_e32 v7, v217, v7
	v_mul_f32_e32 v8, v217, v8
	v_mul_f32_e32 v9, v217, v9
	v_fma_f32 v6, v78, v6, v108
	v_fma_f32 v7, v79, v7, v109
	v_fma_f32 v8, v80, v8, v110
	v_fma_f32 v9, v81, v9, v111
	ds_write_b128 v248, v[6:9] offset:12416
	v_sub_f32_e32 v2, v2, v213
	v_sub_f32_e32 v3, v3, v213
	v_sub_f32_e32 v4, v4, v213
	v_sub_f32_e32 v5, v5, v213
	v_mul_f32_e32 v2, v217, v2
	v_mul_f32_e32 v3, v217, v3
	v_mul_f32_e32 v4, v217, v4
	v_mul_f32_e32 v5, v217, v5
	v_fma_f32 v2, v82, v2, v172
	v_fma_f32 v3, v83, v3, v173
	v_fma_f32 v4, v84, v4, v174
	v_fma_f32 v5, v85, v5, v175
	ds_write_b128 v248, v[2:5] offset:12480
	s_waitcnt lgkmcnt(0)
	ds_read_b128 v[66:69], v249 offset:0
	ds_read_b128 v[74:77], v249 offset:1024
	ds_read_b128 v[78:81], v249 offset:2048
	ds_read_b128 v[82:85], v249 offset:3072
	ds_read_b128 v[90:93], v249 offset:4096
	ds_read_b128 v[94:97], v249 offset:5120
	ds_read_b128 v[108:111], v249 offset:6144
	ds_read_b128 v[172:175], v249 offset:7168
	s_waitcnt lgkmcnt(7)
	global_store_dwordx4 v250, v[66:69], s[26:27]
	s_waitcnt lgkmcnt(6)
	v_add_u32_e32 v251, 0x4000, v250
	global_store_dwordx4 v251, v[74:77], s[26:27]
	s_waitcnt lgkmcnt(5)
	v_add_u32_e32 v251, 0x8000, v250
	global_store_dwordx4 v251, v[78:81], s[26:27]
	s_waitcnt lgkmcnt(4)
	v_add_u32_e32 v251, 0xc000, v250
	global_store_dwordx4 v251, v[82:85], s[26:27]
	s_waitcnt lgkmcnt(3)
	v_add_u32_e32 v251, 0x10000, v250
	global_store_dwordx4 v251, v[90:93], s[26:27]
	s_waitcnt lgkmcnt(2)
	v_add_u32_e32 v251, 0x14000, v250
	global_store_dwordx4 v251, v[94:97], s[26:27]
	s_waitcnt lgkmcnt(1)
	v_add_u32_e32 v251, 0x18000, v250
	global_store_dwordx4 v251, v[108:111], s[26:27]
	s_waitcnt lgkmcnt(0)
	v_add_u32_e32 v251, 0x1c000, v250
	global_store_dwordx4 v251, v[172:175], s[26:27]
	s_nop 1
	ds_read_b128 v[66:69], v249 offset:8192
	ds_read_b128 v[74:77], v249 offset:9216
	ds_read_b128 v[78:81], v249 offset:10240
	ds_read_b128 v[82:85], v249 offset:11264
	ds_read_b128 v[90:93], v249 offset:12288
	ds_read_b128 v[94:97], v249 offset:13312
	ds_read_b128 v[108:111], v249 offset:14336
	ds_read_b128 v[172:175], v249 offset:15360
	s_waitcnt lgkmcnt(7)
	v_add_u32_e32 v251, 0x20000, v250
	global_store_dwordx4 v251, v[66:69], s[26:27]
	s_waitcnt lgkmcnt(6)
	v_add_u32_e32 v251, 0x24000, v250
	global_store_dwordx4 v251, v[74:77], s[26:27]
	s_waitcnt lgkmcnt(5)
	v_add_u32_e32 v251, 0x28000, v250
	global_store_dwordx4 v251, v[78:81], s[26:27]
	s_waitcnt lgkmcnt(4)
	v_add_u32_e32 v251, 0x2c000, v250
	global_store_dwordx4 v251, v[82:85], s[26:27]
	s_waitcnt lgkmcnt(3)
	v_add_u32_e32 v251, 0x30000, v250
	global_store_dwordx4 v251, v[90:93], s[26:27]
	s_waitcnt lgkmcnt(2)
	v_add_u32_e32 v251, 0x34000, v250
	global_store_dwordx4 v251, v[94:97], s[26:27]
	s_waitcnt lgkmcnt(1)
	v_add_u32_e32 v251, 0x38000, v250
	global_store_dwordx4 v251, v[108:111], s[26:27]
	s_waitcnt lgkmcnt(0)
	v_add_u32_e32 v251, 0x3c000, v250
	global_store_dwordx4 v251, v[172:175], s[26:27]
	s_nop 1
	s_add_u32 s44, s94, 0x7b48000
	s_addc_u32 s45, s95, 0
	s_waitcnt vmcnt(16)
	v_add_f32_e32 v226, 1.0, v226
	v_add_f32_e32 v227, 1.0, v227
	v_add_f32_e32 v228, 1.0, v228
	v_add_f32_e32 v229, 1.0, v229
	v_add_f32_e32 v230, 1.0, v230
	v_add_f32_e32 v231, 1.0, v231
	v_add_f32_e32 v232, 1.0, v232
	v_add_f32_e32 v233, 1.0, v233
	v_add_f32_e32 v234, 1.0, v234
	v_add_f32_e32 v235, 1.0, v235
	v_add_f32_e32 v236, 1.0, v236
	v_add_f32_e32 v237, 1.0, v237
	v_add_f32_e32 v238, 1.0, v238
	v_add_f32_e32 v239, 1.0, v239
	v_add_f32_e32 v240, 1.0, v240
	v_add_f32_e32 v241, 1.0, v241
	v_and_b32_e32 v251, 7, v246
	v_lshlrev_b32_e32 v251, 1, v251
	v_or_b32_e32 v218, 0, v247
	v_xor_b32_e32 v218, v218, v251
	v_lshlrev_b32_e32 v218, 3, v218
	v_lshl_add_u32 v218, v246, 7, v218
	v_add_u32_e32 v218, s64, v218
	v_or_b32_e32 v219, 4, v247
	v_xor_b32_e32 v219, v219, v251
	v_lshlrev_b32_e32 v219, 3, v219
	v_lshl_add_u32 v219, v246, 7, v219
	v_add_u32_e32 v219, s64, v219
	v_or_b32_e32 v220, 8, v247
	v_xor_b32_e32 v220, v220, v251
	v_lshlrev_b32_e32 v220, 3, v220
	v_lshl_add_u32 v220, v246, 7, v220
	v_add_u32_e32 v220, s64, v220
	v_or_b32_e32 v221, 12, v247
	v_xor_b32_e32 v221, v221, v251
	v_lshlrev_b32_e32 v221, 3, v221
	v_lshl_add_u32 v221, v246, 7, v221
	v_add_u32_e32 v221, s64, v221
	v_lshrrev_b32_e32 v248, 3, v222
	v_and_b32_e32 v251, 7, v222
	v_xor_b32_e32 v251, v251, v248
	v_add_u32_e32 v248, s36, v248
	v_lshlrev_b32_e32 v248, 11, v248
	v_lshl_add_u32 v248, v251, 4, v248
	s_lshl_b32 s65, s37, 1
	v_add_u32_e32 v248, s65, v248
	v_fma_f32 v62, v226, v62, v38
	v_fma_f32 v63, v227, v63, v39
	v_fma_f32 v64, v228, v64, v40
	v_fma_f32 v65, v229, v65, v41
	v_cvt_pk_bf16_f32 v62, v62, v63
	v_cvt_pk_bf16_f32 v63, v64, v65
	ds_write_b64 v218, v[62:63] offset:0
	v_fma_f32 v86, v230, v86, v42
	v_fma_f32 v87, v231, v87, v43
	v_fma_f32 v88, v232, v88, v44
	v_fma_f32 v89, v233, v89, v45
	v_cvt_pk_bf16_f32 v86, v86, v87
	v_cvt_pk_bf16_f32 v87, v88, v89
	ds_write_b64 v219, v[86:87] offset:0
	v_fma_f32 v70, v234, v70, v46
	v_fma_f32 v71, v235, v71, v47
	v_fma_f32 v72, v236, v72, v48
	v_fma_f32 v73, v237, v73, v49
	v_cvt_pk_bf16_f32 v70, v70, v71
	v_cvt_pk_bf16_f32 v71, v72, v73
	ds_write_b64 v220, v[70:71] offset:0
	v_fma_f32 v176, v238, v176, v50
	v_fma_f32 v177, v239, v177, v51
	v_fma_f32 v178, v240, v178, v52
	v_fma_f32 v179, v241, v179, v53
	v_cvt_pk_bf16_f32 v176, v176, v177
	v_cvt_pk_bf16_f32 v177, v178, v179
	ds_write_b64 v221, v[176:177] offset:0
	v_fma_f32 v202, v226, v202, v38
	v_fma_f32 v203, v227, v203, v39
	v_fma_f32 v204, v228, v204, v40
	v_fma_f32 v205, v229, v205, v41
	v_cvt_pk_bf16_f32 v202, v202, v203
	v_cvt_pk_bf16_f32 v203, v204, v205
	ds_write_b64 v218, v[202:203] offset:2048
	v_fma_f32 v54, v230, v54, v42
	v_fma_f32 v55, v231, v55, v43
	v_fma_f32 v56, v232, v56, v44
	v_fma_f32 v57, v233, v57, v45
	v_cvt_pk_bf16_f32 v54, v54, v55
	v_cvt_pk_bf16_f32 v55, v56, v57
	ds_write_b64 v219, v[54:55] offset:2048
	v_fma_f32 v58, v234, v58, v46
	v_fma_f32 v59, v235, v59, v47
	v_fma_f32 v60, v236, v60, v48
	v_fma_f32 v61, v237, v61, v49
	v_cvt_pk_bf16_f32 v58, v58, v59
	v_cvt_pk_bf16_f32 v59, v60, v61
	ds_write_b64 v220, v[58:59] offset:2048
	v_fma_f32 v34, v238, v34, v50
	v_fma_f32 v35, v239, v35, v51
	v_fma_f32 v36, v240, v36, v52
	v_fma_f32 v37, v241, v37, v53
	v_cvt_pk_bf16_f32 v34, v34, v35
	v_cvt_pk_bf16_f32 v35, v36, v37
	ds_write_b64 v221, v[34:35] offset:2048
	v_fma_f32 v30, v226, v30, v38
	v_fma_f32 v31, v227, v31, v39
	v_fma_f32 v32, v228, v32, v40
	v_fma_f32 v33, v229, v33, v41
	v_cvt_pk_bf16_f32 v30, v30, v31
	v_cvt_pk_bf16_f32 v31, v32, v33
	ds_write_b64 v218, v[30:31] offset:4096
	v_fma_f32 v26, v230, v26, v42
	v_fma_f32 v27, v231, v27, v43
	v_fma_f32 v28, v232, v28, v44
	v_fma_f32 v29, v233, v29, v45
	v_cvt_pk_bf16_f32 v26, v26, v27
	v_cvt_pk_bf16_f32 v27, v28, v29
	ds_write_b64 v219, v[26:27] offset:4096
	v_fma_f32 v22, v234, v22, v46
	v_fma_f32 v23, v235, v23, v47
	v_fma_f32 v24, v236, v24, v48
	v_fma_f32 v25, v237, v25, v49
	v_cvt_pk_bf16_f32 v22, v22, v23
	v_cvt_pk_bf16_f32 v23, v24, v25
	ds_write_b64 v220, v[22:23] offset:4096
	v_fma_f32 v18, v238, v18, v50
	v_fma_f32 v19, v239, v19, v51
	v_fma_f32 v20, v240, v20, v52
	v_fma_f32 v21, v241, v21, v53
	v_cvt_pk_bf16_f32 v18, v18, v19
	v_cvt_pk_bf16_f32 v19, v20, v21
	ds_write_b64 v221, v[18:19] offset:4096
	v_fma_f32 v14, v226, v14, v38
	v_fma_f32 v15, v227, v15, v39
	v_fma_f32 v16, v228, v16, v40
	v_fma_f32 v17, v229, v17, v41
	v_cvt_pk_bf16_f32 v14, v14, v15
	v_cvt_pk_bf16_f32 v15, v16, v17
	ds_write_b64 v218, v[14:15] offset:6144
	v_fma_f32 v10, v230, v10, v42
	v_fma_f32 v11, v231, v11, v43
	v_fma_f32 v12, v232, v12, v44
	v_fma_f32 v13, v233, v13, v45
	v_cvt_pk_bf16_f32 v10, v10, v11
	v_cvt_pk_bf16_f32 v11, v12, v13
	ds_write_b64 v219, v[10:11] offset:6144
	v_fma_f32 v6, v234, v6, v46
	v_fma_f32 v7, v235, v7, v47
	v_fma_f32 v8, v236, v8, v48
	v_fma_f32 v9, v237, v9, v49
	v_cvt_pk_bf16_f32 v6, v6, v7
	v_cvt_pk_bf16_f32 v7, v8, v9
	ds_write_b64 v220, v[6:7] offset:6144
	v_fma_f32 v2, v238, v2, v50
	v_fma_f32 v3, v239, v3, v51
	v_fma_f32 v4, v240, v4, v52
	v_fma_f32 v5, v241, v5, v53
	v_cvt_pk_bf16_f32 v2, v2, v3
	v_cvt_pk_bf16_f32 v3, v4, v5
	ds_write_b64 v221, v[2:3] offset:6144
	s_waitcnt lgkmcnt(0)
	ds_read_b128 v[66:69], v249 offset:0
	ds_read_b128 v[74:77], v249 offset:1024
	ds_read_b128 v[78:81], v249 offset:2048
	ds_read_b128 v[82:85], v249 offset:3072
	ds_read_b128 v[90:93], v249 offset:4096
	ds_read_b128 v[94:97], v249 offset:5120
	ds_read_b128 v[108:111], v249 offset:6144
	ds_read_b128 v[172:175], v249 offset:7168
	s_waitcnt lgkmcnt(7)
	global_store_dwordx4 v248, v[66:69], s[44:45] sc1
	s_waitcnt lgkmcnt(6)
	v_add_u32_e32 v251, 0x4000, v248
	global_store_dwordx4 v251, v[74:77], s[44:45] sc1
	s_waitcnt lgkmcnt(5)
	v_add_u32_e32 v251, 0x8000, v248
	global_store_dwordx4 v251, v[78:81], s[44:45] sc1
	s_waitcnt lgkmcnt(4)
	v_add_u32_e32 v251, 0xc000, v248
	global_store_dwordx4 v251, v[82:85], s[44:45] sc1
	s_waitcnt lgkmcnt(3)
	v_add_u32_e32 v251, 0x10000, v248
	global_store_dwordx4 v251, v[90:93], s[44:45] sc1
	s_waitcnt lgkmcnt(2)
	v_add_u32_e32 v251, 0x14000, v248
	global_store_dwordx4 v251, v[94:97], s[44:45] sc1
	s_waitcnt lgkmcnt(1)
	v_add_u32_e32 v251, 0x18000, v248
	global_store_dwordx4 v251, v[108:111], s[44:45] sc1
	s_waitcnt lgkmcnt(0)
	v_add_u32_e32 v251, 0x1c000, v248
	global_store_dwordx4 v251, v[172:175], s[44:45] sc1
	s_waitcnt vmcnt(0)
	s_barrier
	v_readfirstlane_b32 s6, v137
	s_cmp_lt_u32 s6, 64
	s_cbranch_scc0 .Lln1_nodone
	s_mul_hi_i32 s6, s60, 0x2aaaaaab
	s_lshr_b32 s13, s6, 31
	s_ashr_i32 s6, s6, 2
	s_add_i32 s6, s6, s13
	s_mul_i32 s13, s6, 24
	s_sub_i32 s13, s60, s13
	s_lshl_b32 s13, s13, 3
	s_add_i32 s13, s13, s6
	s_lshl_b32 s13, s13, 4
	v_readlane_b32 s14, v255, 40
	s_add_i32 s14, s14, 0x5d0e1000
	v_mov_b32_e32 v247, s13
	v_mov_b32_e32 v248, s14
	v_mov_b32_e32 v249, s14
	v_mov_b32_e32 v250, s14
	v_mov_b32_e32 v251, s14
	s_add_u32 s36, s94, 0xcbc8000
	s_addc_u32 s37, s95, 0
	s_mov_b64 exec, 1
	global_store_dwordx4 v247, v[248:251], s[36:37] sc1
	s_mov_b64 exec, -1

.Lln2_nomod:
	v_mov_b32_e32 v206, v250
	v_mov_b32_e32 v207, v252
	v_mul_f32_e32 v208, 0x3a800000, v206
	v_mul_f32_e32 v209, v208, v208
	v_mov_b32_e32 v216, 0x3a800000
	v_fma_f32 v209, v207, v216, -v209
	v_max_f32_e32 v209, 0, v209
	v_add_f32_e32 v209, 0x3727c5ac, v209
	v_rsq_f32_e32 v209, v209
	v_mov_b32_e32 v210, v208
	v_mov_b32_e32 v211, v208
	v_mov_b32_e32 v214, v209
	v_mov_b32_e32 v215, v209
	s_nop 1
	v_permlane16_swap_b32_e32 v210, v211
	v_permlane16_swap_b32_e32 v214, v215
	v_mov_b32_e32 v212, v210
	v_mov_b32_e32 v213, v211
	v_mov_b32_e32 v216, v214
	v_mov_b32_e32 v217, v215
	s_nop 1
	v_permlane32_swap_b32_e32 v210, v212
	v_permlane32_swap_b32_e32 v211, v213
	v_permlane32_swap_b32_e32 v214, v216
	v_permlane32_swap_b32_e32 v215, v217
	s_cmp_eq_u32 s53, 3
	s_cselect_b32 s26, s92, s26
	s_cselect_b32 s27, s93, s27
	v_readfirstlane_b32 s54, v137
	s_lshr_b32 s54, s54, 6
	s_lshl_b32 s54, s54, 14
	v_and_b32_e32 v222, 63, v137
	v_and_b32_e32 v246, 15, v222
	v_lshrrev_b32_e32 v247, 4, v222
	v_and_b32_e32 v248, 3, v246
	v_xor_b32_e32 v248, v248, v247
	v_lshlrev_b32_e32 v248, 4, v248
	v_lshl_add_u32 v248, v246, 8, v248
	v_add_u32_e32 v248, s54, v248
	v_lshl_add_u32 v249, v222, 4, s54
	v_add_u32_e32 v250, s50, v247
	v_lshlrev_b32_e32 v250, 12, v250
	v_xor_b32_e32 v251, v246, v247
	v_lshl_add_u32 v250, v251, 4, v250
	s_lshl_b32 s55, s51, 2
	v_add_u32_e32 v250, s55, v250
	v_sub_f32_e32 v62, v62, v210
	v_sub_f32_e32 v63, v63, v210
	v_sub_f32_e32 v64, v64, v210
	v_sub_f32_e32 v65, v65, v210
	v_mul_f32_e32 v62, v214, v62
	v_mul_f32_e32 v63, v214, v63
	v_mul_f32_e32 v64, v214, v64
	v_mul_f32_e32 v65, v214, v65
	v_fma_f32 v62, v66, v62, v90
	v_fma_f32 v63, v67, v63, v91
	v_fma_f32 v64, v68, v64, v92
	v_fma_f32 v65, v69, v65, v93
	ds_write_b128 v248, v[62:65] offset:0
	v_sub_f32_e32 v86, v86, v210
	v_sub_f32_e32 v87, v87, v210
	v_sub_f32_e32 v88, v88, v210
	v_sub_f32_e32 v89, v89, v210
	v_mul_f32_e32 v86, v214, v86
	v_mul_f32_e32 v87, v214, v87
	v_mul_f32_e32 v88, v214, v88
	v_mul_f32_e32 v89, v214, v89
	v_fma_f32 v86, v74, v86, v94
	v_fma_f32 v87, v75, v87, v95
	v_fma_f32 v88, v76, v88, v96
	v_fma_f32 v89, v77, v89, v97
	ds_write_b128 v248, v[86:89] offset:64
	v_sub_f32_e32 v70, v70, v210
	v_sub_f32_e32 v71, v71, v210
	v_sub_f32_e32 v72, v72, v210
	v_sub_f32_e32 v73, v73, v210
	v_mul_f32_e32 v70, v214, v70
	v_mul_f32_e32 v71, v214, v71
	v_mul_f32_e32 v72, v214, v72
	v_mul_f32_e32 v73, v214, v73
	v_fma_f32 v70, v78, v70, v108
	v_fma_f32 v71, v79, v71, v109
	v_fma_f32 v72, v80, v72, v110
	v_fma_f32 v73, v81, v73, v111
	ds_write_b128 v248, v[70:73] offset:128
	v_sub_f32_e32 v176, v176, v210
	v_sub_f32_e32 v177, v177, v210
	v_sub_f32_e32 v178, v178, v210
	v_sub_f32_e32 v179, v179, v210
	v_mul_f32_e32 v176, v214, v176
	v_mul_f32_e32 v177, v214, v177
	v_mul_f32_e32 v178, v214, v178
	v_mul_f32_e32 v179, v214, v179
	v_fma_f32 v176, v82, v176, v172
	v_fma_f32 v177, v83, v177, v173
	v_fma_f32 v178, v84, v178, v174
	v_fma_f32 v179, v85, v179, v175
	ds_write_b128 v248, v[176:179] offset:192
	v_sub_f32_e32 v202, v202, v211
	v_sub_f32_e32 v203, v203, v211
	v_sub_f32_e32 v204, v204, v211
	v_sub_f32_e32 v205, v205, v211
	v_mul_f32_e32 v202, v215, v202
	v_mul_f32_e32 v203, v215, v203
	v_mul_f32_e32 v204, v215, v204
	v_mul_f32_e32 v205, v215, v205
	v_fma_f32 v202, v66, v202, v90
	v_fma_f32 v203, v67, v203, v91
	v_fma_f32 v204, v68, v204, v92
	v_fma_f32 v205, v69, v205, v93
	ds_write_b128 v248, v[202:205] offset:4096
	v_sub_f32_e32 v54, v54, v211
	v_sub_f32_e32 v55, v55, v211
	v_sub_f32_e32 v56, v56, v211
	v_sub_f32_e32 v57, v57, v211
	v_mul_f32_e32 v54, v215, v54
	v_mul_f32_e32 v55, v215, v55
	v_mul_f32_e32 v56, v215, v56
	v_mul_f32_e32 v57, v215, v57
	v_fma_f32 v54, v74, v54, v94
	v_fma_f32 v55, v75, v55, v95
	v_fma_f32 v56, v76, v56, v96
	v_fma_f32 v57, v77, v57, v97
	ds_write_b128 v248, v[54:57] offset:4160
	v_sub_f32_e32 v58, v58, v211
	v_sub_f32_e32 v59, v59, v211
	v_sub_f32_e32 v60, v60, v211
	v_sub_f32_e32 v61, v61, v211
	v_mul_f32_e32 v58, v215, v58
	v_mul_f32_e32 v59, v215, v59
	v_mul_f32_e32 v60, v215, v60
	v_mul_f32_e32 v61, v215, v61
	v_fma_f32 v58, v78, v58, v108
	v_fma_f32 v59, v79, v59, v109
	v_fma_f32 v60, v80, v60, v110
	v_fma_f32 v61, v81, v61, v111
	ds_write_b128 v248, v[58:61] offset:4224
	v_sub_f32_e32 v34, v34, v211
	v_sub_f32_e32 v35, v35, v211
	v_sub_f32_e32 v36, v36, v211
	v_sub_f32_e32 v37, v37, v211
	v_mul_f32_e32 v34, v215, v34
	v_mul_f32_e32 v35, v215, v35
	v_mul_f32_e32 v36, v215, v36
	v_mul_f32_e32 v37, v215, v37
	v_fma_f32 v34, v82, v34, v172
	v_fma_f32 v35, v83, v35, v173
	v_fma_f32 v36, v84, v36, v174
	v_fma_f32 v37, v85, v37, v175
	ds_write_b128 v248, v[34:37] offset:4288
	v_sub_f32_e32 v30, v30, v212
	v_sub_f32_e32 v31, v31, v212
	v_sub_f32_e32 v32, v32, v212
	v_sub_f32_e32 v33, v33, v212
	v_mul_f32_e32 v30, v216, v30
	v_mul_f32_e32 v31, v216, v31
	v_mul_f32_e32 v32, v216, v32
	v_mul_f32_e32 v33, v216, v33
	v_fma_f32 v30, v66, v30, v90
	v_fma_f32 v31, v67, v31, v91
	v_fma_f32 v32, v68, v32, v92
	v_fma_f32 v33, v69, v33, v93
	ds_write_b128 v248, v[30:33] offset:8192
	v_sub_f32_e32 v26, v26, v212
	v_sub_f32_e32 v27, v27, v212
	v_sub_f32_e32 v28, v28, v212
	v_sub_f32_e32 v29, v29, v212
	v_mul_f32_e32 v26, v216, v26
	v_mul_f32_e32 v27, v216, v27
	v_mul_f32_e32 v28, v216, v28
	v_mul_f32_e32 v29, v216, v29
	v_fma_f32 v26, v74, v26, v94
	v_fma_f32 v27, v75, v27, v95
	v_fma_f32 v28, v76, v28, v96
	v_fma_f32 v29, v77, v29, v97
	ds_write_b128 v248, v[26:29] offset:8256
	v_sub_f32_e32 v22, v22, v212
	v_sub_f32_e32 v23, v23, v212
	v_sub_f32_e32 v24, v24, v212
	v_sub_f32_e32 v25, v25, v212
	v_mul_f32_e32 v22, v216, v22
	v_mul_f32_e32 v23, v216, v23
	v_mul_f32_e32 v24, v216, v24
	v_mul_f32_e32 v25, v216, v25
	v_fma_f32 v22, v78, v22, v108
	v_fma_f32 v23, v79, v23, v109
	v_fma_f32 v24, v80, v24, v110
	v_fma_f32 v25, v81, v25, v111
	ds_write_b128 v248, v[22:25] offset:8320
	v_sub_f32_e32 v18, v18, v212
	v_sub_f32_e32 v19, v19, v212
	v_sub_f32_e32 v20, v20, v212
	v_sub_f32_e32 v21, v21, v212
	v_mul_f32_e32 v18, v216, v18
	v_mul_f32_e32 v19, v216, v19
	v_mul_f32_e32 v20, v216, v20
	v_mul_f32_e32 v21, v216, v21
	v_fma_f32 v18, v82, v18, v172
	v_fma_f32 v19, v83, v19, v173
	v_fma_f32 v20, v84, v20, v174
	v_fma_f32 v21, v85, v21, v175
	ds_write_b128 v248, v[18:21] offset:8384
	v_sub_f32_e32 v14, v14, v213
	v_sub_f32_e32 v15, v15, v213
	v_sub_f32_e32 v16, v16, v213
	v_sub_f32_e32 v17, v17, v213
	v_mul_f32_e32 v14, v217, v14
	v_mul_f32_e32 v15, v217, v15
	v_mul_f32_e32 v16, v217, v16
	v_mul_f32_e32 v17, v217, v17
	v_fma_f32 v14, v66, v14, v90
	v_fma_f32 v15, v67, v15, v91
	v_fma_f32 v16, v68, v16, v92
	v_fma_f32 v17, v69, v17, v93
	ds_write_b128 v248, v[14:17] offset:12288
	v_sub_f32_e32 v10, v10, v213
	v_sub_f32_e32 v11, v11, v213
	v_sub_f32_e32 v12, v12, v213
	v_sub_f32_e32 v13, v13, v213
	v_mul_f32_e32 v10, v217, v10
	v_mul_f32_e32 v11, v217, v11
	v_mul_f32_e32 v12, v217, v12
	v_mul_f32_e32 v13, v217, v13
	v_fma_f32 v10, v74, v10, v94
	v_fma_f32 v11, v75, v11, v95
	v_fma_f32 v12, v76, v12, v96
	v_fma_f32 v13, v77, v13, v97
	ds_write_b128 v248, v[10:13] offset:12352
	v_sub_f32_e32 v6, v6, v213
	v_sub_f32_e32 v7, v7, v213
	v_sub_f32_e32 v8, v8, v213
	v_sub_f32_e32 v9, v9, v213
	v_mul_f32_e32 v6, v217, v6
	v_mul_f32_e32 v7, v217, v7
	v_mul_f32_e32 v8, v217, v8
	v_mul_f32_e32 v9, v217, v9
	v_fma_f32 v6, v78, v6, v108
	v_fma_f32 v7, v79, v7, v109
	v_fma_f32 v8, v80, v8, v110
	v_fma_f32 v9, v81, v9, v111
	ds_write_b128 v248, v[6:9] offset:12416
	v_sub_f32_e32 v2, v2, v213
	v_sub_f32_e32 v3, v3, v213
	v_sub_f32_e32 v4, v4, v213
	v_sub_f32_e32 v5, v5, v213
	v_mul_f32_e32 v2, v217, v2
	v_mul_f32_e32 v3, v217, v3
	v_mul_f32_e32 v4, v217, v4
	v_mul_f32_e32 v5, v217, v5
	v_fma_f32 v2, v82, v2, v172
	v_fma_f32 v3, v83, v3, v173
	v_fma_f32 v4, v84, v4, v174
	v_fma_f32 v5, v85, v5, v175
	ds_write_b128 v248, v[2:5] offset:12480
	s_waitcnt lgkmcnt(0)
	ds_read_b128 v[66:69], v249 offset:0
	ds_read_b128 v[74:77], v249 offset:1024
	ds_read_b128 v[78:81], v249 offset:2048
	ds_read_b128 v[82:85], v249 offset:3072
	ds_read_b128 v[90:93], v249 offset:4096
	ds_read_b128 v[94:97], v249 offset:5120
	ds_read_b128 v[108:111], v249 offset:6144
	ds_read_b128 v[172:175], v249 offset:7168
	s_waitcnt lgkmcnt(7)
	global_store_dwordx4 v250, v[66:69], s[26:27]
	s_waitcnt lgkmcnt(6)
	v_add_u32_e32 v251, 0x4000, v250
	global_store_dwordx4 v251, v[74:77], s[26:27]
	s_waitcnt lgkmcnt(5)
	v_add_u32_e32 v251, 0x8000, v250
	global_store_dwordx4 v251, v[78:81], s[26:27]
	s_waitcnt lgkmcnt(4)
	v_add_u32_e32 v251, 0xc000, v250
	global_store_dwordx4 v251, v[82:85], s[26:27]
	s_waitcnt lgkmcnt(3)
	v_add_u32_e32 v251, 0x10000, v250
	global_store_dwordx4 v251, v[90:93], s[26:27]
	s_waitcnt lgkmcnt(2)
	v_add_u32_e32 v251, 0x14000, v250
	global_store_dwordx4 v251, v[94:97], s[26:27]
	s_waitcnt lgkmcnt(1)
	v_add_u32_e32 v251, 0x18000, v250
	global_store_dwordx4 v251, v[108:111], s[26:27]
	s_waitcnt lgkmcnt(0)
	v_add_u32_e32 v251, 0x1c000, v250
	global_store_dwordx4 v251, v[172:175], s[26:27]
	s_nop 1
	ds_read_b128 v[66:69], v249 offset:8192
	ds_read_b128 v[74:77], v249 offset:9216
	ds_read_b128 v[78:81], v249 offset:10240
	ds_read_b128 v[82:85], v249 offset:11264
	ds_read_b128 v[90:93], v249 offset:12288
	ds_read_b128 v[94:97], v249 offset:13312
	ds_read_b128 v[108:111], v249 offset:14336
	ds_read_b128 v[172:175], v249 offset:15360
	s_waitcnt lgkmcnt(7)
	v_add_u32_e32 v251, 0x20000, v250
	global_store_dwordx4 v251, v[66:69], s[26:27]
	s_waitcnt lgkmcnt(6)
	v_add_u32_e32 v251, 0x24000, v250
	global_store_dwordx4 v251, v[74:77], s[26:27]
	s_waitcnt lgkmcnt(5)
	v_add_u32_e32 v251, 0x28000, v250
	global_store_dwordx4 v251, v[78:81], s[26:27]
	s_waitcnt lgkmcnt(4)
	v_add_u32_e32 v251, 0x2c000, v250
	global_store_dwordx4 v251, v[82:85], s[26:27]
	s_waitcnt lgkmcnt(3)
	v_add_u32_e32 v251, 0x30000, v250
	global_store_dwordx4 v251, v[90:93], s[26:27]
	s_waitcnt lgkmcnt(2)
	v_add_u32_e32 v251, 0x34000, v250
	global_store_dwordx4 v251, v[94:97], s[26:27]
	s_waitcnt lgkmcnt(1)
	v_add_u32_e32 v251, 0x38000, v250
	global_store_dwordx4 v251, v[108:111], s[26:27]
	s_waitcnt lgkmcnt(0)
	v_add_u32_e32 v251, 0x3c000, v250
	global_store_dwordx4 v251, v[172:175], s[26:27]
	s_nop 1
	s_cmp_eq_u32 s53, 3
	s_cbranch_scc1 .Lln2_end
	s_add_u32 s34, s94, 0x7b48000
	s_addc_u32 s35, s95, 0
	s_waitcnt vmcnt(16)
	v_add_f32_e32 v226, 1.0, v226
	v_add_f32_e32 v227, 1.0, v227
	v_add_f32_e32 v228, 1.0, v228
	v_add_f32_e32 v229, 1.0, v229
	v_add_f32_e32 v230, 1.0, v230
	v_add_f32_e32 v231, 1.0, v231
	v_add_f32_e32 v232, 1.0, v232
	v_add_f32_e32 v233, 1.0, v233
	v_add_f32_e32 v234, 1.0, v234
	v_add_f32_e32 v235, 1.0, v235
	v_add_f32_e32 v236, 1.0, v236
	v_add_f32_e32 v237, 1.0, v237
	v_add_f32_e32 v238, 1.0, v238
	v_add_f32_e32 v239, 1.0, v239
	v_add_f32_e32 v240, 1.0, v240
	v_add_f32_e32 v241, 1.0, v241
	v_and_b32_e32 v251, 7, v246
	v_lshlrev_b32_e32 v251, 1, v251
	v_or_b32_e32 v218, 0, v247
	v_xor_b32_e32 v218, v218, v251
	v_lshlrev_b32_e32 v218, 3, v218
	v_lshl_add_u32 v218, v246, 7, v218
	v_add_u32_e32 v218, s54, v218
	v_or_b32_e32 v219, 4, v247
	v_xor_b32_e32 v219, v219, v251
	v_lshlrev_b32_e32 v219, 3, v219
	v_lshl_add_u32 v219, v246, 7, v219
	v_add_u32_e32 v219, s54, v219
	v_or_b32_e32 v220, 8, v247
	v_xor_b32_e32 v220, v220, v251
	v_lshlrev_b32_e32 v220, 3, v220
	v_lshl_add_u32 v220, v246, 7, v220
	v_add_u32_e32 v220, s54, v220
	v_or_b32_e32 v221, 12, v247
	v_xor_b32_e32 v221, v221, v251
	v_lshlrev_b32_e32 v221, 3, v221
	v_lshl_add_u32 v221, v246, 7, v221
	v_add_u32_e32 v221, s54, v221
	v_lshrrev_b32_e32 v248, 3, v222
	v_and_b32_e32 v251, 7, v222
	v_xor_b32_e32 v251, v251, v248
	v_add_u32_e32 v248, s50, v248
	v_lshlrev_b32_e32 v248, 11, v248
	v_lshl_add_u32 v248, v251, 4, v248
	s_lshl_b32 s55, s51, 1
	v_add_u32_e32 v248, s55, v248
	v_fma_f32 v62, v226, v62, v38
	v_fma_f32 v63, v227, v63, v39
	v_fma_f32 v64, v228, v64, v40
	v_fma_f32 v65, v229, v65, v41
	v_cvt_pk_bf16_f32 v62, v62, v63
	v_cvt_pk_bf16_f32 v63, v64, v65
	ds_write_b64 v218, v[62:63] offset:0
	v_fma_f32 v86, v230, v86, v42
	v_fma_f32 v87, v231, v87, v43
	v_fma_f32 v88, v232, v88, v44
	v_fma_f32 v89, v233, v89, v45
	v_cvt_pk_bf16_f32 v86, v86, v87
	v_cvt_pk_bf16_f32 v87, v88, v89
	ds_write_b64 v219, v[86:87] offset:0
	v_fma_f32 v70, v234, v70, v46
	v_fma_f32 v71, v235, v71, v47
	v_fma_f32 v72, v236, v72, v48
	v_fma_f32 v73, v237, v73, v49
	v_cvt_pk_bf16_f32 v70, v70, v71
	v_cvt_pk_bf16_f32 v71, v72, v73
	ds_write_b64 v220, v[70:71] offset:0
	v_fma_f32 v176, v238, v176, v50
	v_fma_f32 v177, v239, v177, v51
	v_fma_f32 v178, v240, v178, v52
	v_fma_f32 v179, v241, v179, v53
	v_cvt_pk_bf16_f32 v176, v176, v177
	v_cvt_pk_bf16_f32 v177, v178, v179
	ds_write_b64 v221, v[176:177] offset:0
	v_fma_f32 v202, v226, v202, v38
	v_fma_f32 v203, v227, v203, v39
	v_fma_f32 v204, v228, v204, v40
	v_fma_f32 v205, v229, v205, v41
	v_cvt_pk_bf16_f32 v202, v202, v203
	v_cvt_pk_bf16_f32 v203, v204, v205
	ds_write_b64 v218, v[202:203] offset:2048
	v_fma_f32 v54, v230, v54, v42
	v_fma_f32 v55, v231, v55, v43
	v_fma_f32 v56, v232, v56, v44
	v_fma_f32 v57, v233, v57, v45
	v_cvt_pk_bf16_f32 v54, v54, v55
	v_cvt_pk_bf16_f32 v55, v56, v57
	ds_write_b64 v219, v[54:55] offset:2048
	v_fma_f32 v58, v234, v58, v46
	v_fma_f32 v59, v235, v59, v47
	v_fma_f32 v60, v236, v60, v48
	v_fma_f32 v61, v237, v61, v49
	v_cvt_pk_bf16_f32 v58, v58, v59
	v_cvt_pk_bf16_f32 v59, v60, v61
	ds_write_b64 v220, v[58:59] offset:2048
	v_fma_f32 v34, v238, v34, v50
	v_fma_f32 v35, v239, v35, v51
	v_fma_f32 v36, v240, v36, v52
	v_fma_f32 v37, v241, v37, v53
	v_cvt_pk_bf16_f32 v34, v34, v35
	v_cvt_pk_bf16_f32 v35, v36, v37
	ds_write_b64 v221, v[34:35] offset:2048
	v_fma_f32 v30, v226, v30, v38
	v_fma_f32 v31, v227, v31, v39
	v_fma_f32 v32, v228, v32, v40
	v_fma_f32 v33, v229, v33, v41
	v_cvt_pk_bf16_f32 v30, v30, v31
	v_cvt_pk_bf16_f32 v31, v32, v33
	ds_write_b64 v218, v[30:31] offset:4096
	v_fma_f32 v26, v230, v26, v42
	v_fma_f32 v27, v231, v27, v43
	v_fma_f32 v28, v232, v28, v44
	v_fma_f32 v29, v233, v29, v45
	v_cvt_pk_bf16_f32 v26, v26, v27
	v_cvt_pk_bf16_f32 v27, v28, v29
	ds_write_b64 v219, v[26:27] offset:4096
	v_fma_f32 v22, v234, v22, v46
	v_fma_f32 v23, v235, v23, v47
	v_fma_f32 v24, v236, v24, v48
	v_fma_f32 v25, v237, v25, v49
	v_cvt_pk_bf16_f32 v22, v22, v23
	v_cvt_pk_bf16_f32 v23, v24, v25
	ds_write_b64 v220, v[22:23] offset:4096
	v_fma_f32 v18, v238, v18, v50
	v_fma_f32 v19, v239, v19, v51
	v_fma_f32 v20, v240, v20, v52
	v_fma_f32 v21, v241, v21, v53
	v_cvt_pk_bf16_f32 v18, v18, v19
	v_cvt_pk_bf16_f32 v19, v20, v21
	ds_write_b64 v221, v[18:19] offset:4096
	v_fma_f32 v14, v226, v14, v38
	v_fma_f32 v15, v227, v15, v39
	v_fma_f32 v16, v228, v16, v40
	v_fma_f32 v17, v229, v17, v41
	v_cvt_pk_bf16_f32 v14, v14, v15
	v_cvt_pk_bf16_f32 v15, v16, v17
	ds_write_b64 v218, v[14:15] offset:6144
	v_fma_f32 v10, v230, v10, v42
	v_fma_f32 v11, v231, v11, v43
	v_fma_f32 v12, v232, v12, v44
	v_fma_f32 v13, v233, v13, v45
	v_cvt_pk_bf16_f32 v10, v10, v11
	v_cvt_pk_bf16_f32 v11, v12, v13
	ds_write_b64 v219, v[10:11] offset:6144
	v_fma_f32 v6, v234, v6, v46
	v_fma_f32 v7, v235, v7, v47
	v_fma_f32 v8, v236, v8, v48
	v_fma_f32 v9, v237, v9, v49
	v_cvt_pk_bf16_f32 v6, v6, v7
	v_cvt_pk_bf16_f32 v7, v8, v9
	ds_write_b64 v220, v[6:7] offset:6144
	v_fma_f32 v2, v238, v2, v50
	v_fma_f32 v3, v239, v3, v51
	v_fma_f32 v4, v240, v4, v52
	v_fma_f32 v5, v241, v5, v53
	v_cvt_pk_bf16_f32 v2, v2, v3
	v_cvt_pk_bf16_f32 v3, v4, v5
	ds_write_b64 v221, v[2:3] offset:6144
	s_waitcnt lgkmcnt(0)
	ds_read_b128 v[66:69], v249 offset:0
	ds_read_b128 v[74:77], v249 offset:1024
	ds_read_b128 v[78:81], v249 offset:2048
	ds_read_b128 v[82:85], v249 offset:3072
	ds_read_b128 v[90:93], v249 offset:4096
	ds_read_b128 v[94:97], v249 offset:5120
	ds_read_b128 v[108:111], v249 offset:6144
	ds_read_b128 v[172:175], v249 offset:7168
	s_waitcnt lgkmcnt(7)
	global_store_dwordx4 v248, v[66:69], s[34:35] sc1
	s_waitcnt lgkmcnt(6)
	v_add_u32_e32 v251, 0x4000, v248
	global_store_dwordx4 v251, v[74:77], s[34:35] sc1
	s_waitcnt lgkmcnt(5)
	v_add_u32_e32 v251, 0x8000, v248
	global_store_dwordx4 v251, v[78:81], s[34:35] sc1
	s_waitcnt lgkmcnt(4)
	v_add_u32_e32 v251, 0xc000, v248
	global_store_dwordx4 v251, v[82:85], s[34:35] sc1
	s_waitcnt lgkmcnt(3)
	v_add_u32_e32 v251, 0x10000, v248
	global_store_dwordx4 v251, v[90:93], s[34:35] sc1
	s_waitcnt lgkmcnt(2)
	v_add_u32_e32 v251, 0x14000, v248
	global_store_dwordx4 v251, v[94:97], s[34:35] sc1
	s_waitcnt lgkmcnt(1)
	v_add_u32_e32 v251, 0x18000, v248
	global_store_dwordx4 v251, v[108:111], s[34:35] sc1
	s_waitcnt lgkmcnt(0)
	v_add_u32_e32 v251, 0x1c000, v248
	global_store_dwordx4 v251, v[172:175], s[34:35] sc1
